# EpiResid<false> epilogue: second-half x loads and gate loads issued early through a register ring (one exposed round trip instead of three)
# speedup vs baseline: 1.0022x; 1.0022x over previous
.LBB0_1054:
	v_or_b32_e32 v120, 0x10000, v184
	v_add_u32_e32 v124, 0x10400, v184
	v_add_u32_e32 v136, 0x10800, v184
	v_add_u32_e32 v140, 0x10c00, v184
	ds_read_b128 v[120:123], v120
	ds_read_b128 v[124:127], v124
	ds_read_b128 v[136:139], v136
	ds_read_b128 v[140:143], v140
	s_add_u32 s20, s18, 0xfff00080
	s_addc_u32 s21, s19, -1
	s_cmp_eq_u32 s67, 60
	s_cselect_b32 s23, s5, s21
	s_cselect_b32 s22, s7, s20
	s_cselect_b32 s21, s17, s66
	s_cselect_b32 s20, s64, s65
	v_lshl_add_u64 v[190:191], s[18:19], 0, v[172:173]
	s_add_i32 m0, s29, 0xc000
	ds_read_b128 v[144:147], v169
	ds_read_b128 v[148:151], v169 offset:1024
	ds_read_b128 v[152:155], v169 offset:2048
	ds_read_b128 v[156:159], v169 offset:3072
	ds_read_b128 v[176:179], v169 offset:4096
	ds_read_b128 v[180:183], v169 offset:5120
	ds_read_b128 v[186:189], v169 offset:6144
	ds_read_b128 v[206:209], v169 offset:7168
	global_load_lds_dwordx4 v[190:191], off
	v_lshl_add_u64 v[190:191], s[18:19], 0, v[174:175]
	s_add_i32 m0, s29, 0xe000
	s_nop 0
	global_load_lds_dwordx4 v[190:191], off
	s_waitcnt lgkmcnt(8)
	s_barrier
	s_waitcnt lgkmcnt(0)
	s_setprio 1
	s_waitcnt lgkmcnt(0)
	v_mfma_f32_16x16x32_bf16 v[132:135], v[120:123], v[144:147], v[132:135]
	v_mfma_f32_16x16x32_bf16 v[128:131], v[136:139], v[144:147], v[128:131]
	v_mfma_f32_16x16x32_bf16 v[108:111], v[120:123], v[152:155], v[108:111]
	v_mfma_f32_16x16x32_bf16 v[104:107], v[136:139], v[152:155], v[104:107]
	v_mfma_f32_16x16x32_bf16 v[96:99], v[120:123], v[176:179], v[96:99]
	v_mfma_f32_16x16x32_bf16 v[88:91], v[136:139], v[176:179], v[88:91]
	v_mfma_f32_16x16x32_bf16 v[80:83], v[120:123], v[186:189], v[80:83]
	v_mfma_f32_16x16x32_bf16 v[72:75], v[136:139], v[186:189], v[72:75]
	v_mfma_f32_16x16x32_bf16 v[132:135], v[124:127], v[148:151], v[132:135]
	v_mfma_f32_16x16x32_bf16 v[128:131], v[140:143], v[148:151], v[128:131]
	v_mfma_f32_16x16x32_bf16 v[108:111], v[124:127], v[156:159], v[108:111]
	v_mfma_f32_16x16x32_bf16 v[104:107], v[140:143], v[156:159], v[104:107]
	v_mfma_f32_16x16x32_bf16 v[96:99], v[124:127], v[180:183], v[96:99]
	v_mfma_f32_16x16x32_bf16 v[88:91], v[140:143], v[180:183], v[88:91]
	v_mfma_f32_16x16x32_bf16 v[80:83], v[124:127], v[206:209], v[80:83]
	v_mfma_f32_16x16x32_bf16 v[72:75], v[140:143], v[206:209], v[72:75]
	s_setprio 0
	s_barrier
	v_or_b32_e32 v185, 0x14000, v184
	v_add_u32_e32 v190, 0x14400, v184
	ds_read_b128 v[210:213], v185
	ds_read_b128 v[214:217], v190
	v_add_u32_e32 v185, 0x14800, v184
	v_add_u32_e32 v190, 0x14c00, v184
	s_mov_b32 m0, s31
	ds_read_b128 v[244:247], v185
	ds_read_b128 v[248:251], v190
	v_lshl_add_u64 v[190:191], s[20:21], 0, v[164:165]
	global_load_lds_dwordx4 v[190:191], off
	v_lshl_add_u64 v[218:219], s[20:21], 0, v[160:161]
	s_mov_b32 m0, s34
	s_nop 0
	global_load_lds_dwordx4 v[218:219], off
	s_barrier
	s_waitcnt lgkmcnt(0)
	s_setprio 1
	s_waitcnt lgkmcnt(0)
	v_mfma_f32_16x16x32_bf16 v[116:119], v[210:213], v[144:147], v[116:119]
	v_mfma_f32_16x16x32_bf16 v[112:115], v[244:247], v[144:147], v[112:115]
	v_mfma_f32_16x16x32_bf16 v[100:103], v[210:213], v[152:155], v[100:103]
	v_mfma_f32_16x16x32_bf16 v[92:95], v[244:247], v[152:155], v[92:95]
	v_mfma_f32_16x16x32_bf16 v[84:87], v[210:213], v[176:179], v[84:87]
	v_mfma_f32_16x16x32_bf16 v[76:79], v[244:247], v[176:179], v[76:79]
	v_mfma_f32_16x16x32_bf16 v[68:71], v[210:213], v[186:189], v[68:71]
	v_mfma_f32_16x16x32_bf16 v[64:67], v[244:247], v[186:189], v[64:67]
	v_mfma_f32_16x16x32_bf16 v[116:119], v[214:217], v[148:151], v[116:119]
	v_mfma_f32_16x16x32_bf16 v[112:115], v[248:251], v[148:151], v[112:115]
	v_mfma_f32_16x16x32_bf16 v[100:103], v[214:217], v[156:159], v[100:103]
	v_mfma_f32_16x16x32_bf16 v[92:95], v[248:251], v[156:159], v[92:95]
	v_mfma_f32_16x16x32_bf16 v[84:87], v[214:217], v[180:183], v[84:87]
	v_mfma_f32_16x16x32_bf16 v[76:79], v[248:251], v[180:183], v[76:79]
	v_mfma_f32_16x16x32_bf16 v[68:71], v[214:217], v[206:209], v[68:71]
	v_mfma_f32_16x16x32_bf16 v[64:67], v[248:251], v[206:209], v[64:67]
	s_setprio 0
	s_mov_b32 m0, s29
	v_lshl_add_u64 v[228:229], s[22:23], 0, v[166:167]
	s_barrier
	ds_read_b128 v[144:147], v169 offset:16384
	ds_read_b128 v[148:151], v169 offset:17408
	ds_read_b128 v[152:155], v169 offset:18432
	ds_read_b128 v[156:159], v169 offset:19456
	ds_read_b128 v[176:179], v169 offset:20480
	ds_read_b128 v[180:183], v169 offset:21504
	ds_read_b128 v[186:189], v169 offset:22528
	ds_read_b128 v[206:209], v169 offset:23552
	global_load_lds_dwordx4 v[228:229], off
	v_lshl_add_u64 v[232:233], s[22:23], 0, v[162:163]
	s_mov_b32 m0, s35
	s_nop 0
	global_load_lds_dwordx4 v[232:233], off
	s_barrier
	s_waitcnt lgkmcnt(0)
	s_setprio 1
	s_waitcnt lgkmcnt(0)
	v_mfma_f32_16x16x32_bf16 v[60:63], v[120:123], v[144:147], v[60:63]
	v_mfma_f32_16x16x32_bf16 v[56:59], v[136:139], v[144:147], v[56:59]
	v_mfma_f32_16x16x32_bf16 v[48:51], v[120:123], v[152:155], v[48:51]
	v_mfma_f32_16x16x32_bf16 v[40:43], v[136:139], v[152:155], v[40:43]
	v_mfma_f32_16x16x32_bf16 v[32:35], v[120:123], v[176:179], v[32:35]
	v_mfma_f32_16x16x32_bf16 v[24:27], v[136:139], v[176:179], v[24:27]
	v_mfma_f32_16x16x32_bf16 v[16:19], v[120:123], v[186:189], v[16:19]
	v_mfma_f32_16x16x32_bf16 v[8:11], v[136:139], v[186:189], v[8:11]
	v_mfma_f32_16x16x32_bf16 v[60:63], v[124:127], v[148:151], v[60:63]
	v_mfma_f32_16x16x32_bf16 v[56:59], v[140:143], v[148:151], v[56:59]
	v_mfma_f32_16x16x32_bf16 v[48:51], v[124:127], v[156:159], v[48:51]
	v_mfma_f32_16x16x32_bf16 v[40:43], v[140:143], v[156:159], v[40:43]
	v_mfma_f32_16x16x32_bf16 v[32:35], v[124:127], v[180:183], v[32:35]
	v_mfma_f32_16x16x32_bf16 v[24:27], v[140:143], v[180:183], v[24:27]
	v_mfma_f32_16x16x32_bf16 v[16:19], v[124:127], v[206:209], v[16:19]
	v_mfma_f32_16x16x32_bf16 v[8:11], v[140:143], v[206:209], v[8:11]
	s_setprio 0
	s_barrier
	s_add_u32 s68, s20, 0x100000
	s_addc_u32 s69, s21, 0
	s_mov_b32 m0, s36
	v_lshl_add_u64 v[120:121], s[68:69], 0, v[164:165]
	global_load_lds_dwordx4 v[120:121], off
	v_lshl_add_u64 v[120:121], s[68:69], 0, v[160:161]
	s_mov_b32 m0, s37
	s_nop 0
	global_load_lds_dwordx4 v[120:121], off
	s_waitcnt vmcnt(6)
	s_barrier
	s_setprio 1
	v_mfma_f32_16x16x32_bf16 v[52:55], v[210:213], v[144:147], v[52:55]
	v_mfma_f32_16x16x32_bf16 v[44:47], v[244:247], v[144:147], v[44:47]
	v_mfma_f32_16x16x32_bf16 v[36:39], v[210:213], v[152:155], v[36:39]
	v_mfma_f32_16x16x32_bf16 v[28:31], v[244:247], v[152:155], v[28:31]
	v_mfma_f32_16x16x32_bf16 v[20:23], v[210:213], v[176:179], v[20:23]
	v_mfma_f32_16x16x32_bf16 v[12:15], v[244:247], v[176:179], v[12:15]
	v_mfma_f32_16x16x32_bf16 v[4:7], v[210:213], v[186:189], v[4:7]
	v_mfma_f32_16x16x32_bf16 v[0:3], v[244:247], v[186:189], v[0:3]
	v_mfma_f32_16x16x32_bf16 v[52:55], v[214:217], v[148:151], v[52:55]
	v_mfma_f32_16x16x32_bf16 v[44:47], v[248:251], v[148:151], v[44:47]
	v_mfma_f32_16x16x32_bf16 v[36:39], v[214:217], v[156:159], v[36:39]
	v_mfma_f32_16x16x32_bf16 v[28:31], v[248:251], v[156:159], v[28:31]
	v_mfma_f32_16x16x32_bf16 v[20:23], v[214:217], v[180:183], v[20:23]
	v_mfma_f32_16x16x32_bf16 v[12:15], v[248:251], v[180:183], v[12:15]
	v_mfma_f32_16x16x32_bf16 v[4:7], v[214:217], v[206:209], v[4:7]
	v_mfma_f32_16x16x32_bf16 v[0:3], v[248:251], v[206:209], v[0:3]
	s_setprio 0
	v_or_b32_e32 v120, 0x18000, v184
	v_add_u32_e32 v124, 0x18400, v184
	v_add_u32_e32 v136, 0x18800, v184
	v_add_u32_e32 v140, 0x18c00, v184
	s_barrier
	ds_read_b128 v[120:123], v120
	ds_read_b128 v[124:127], v124
	ds_read_b128 v[136:139], v136
	ds_read_b128 v[140:143], v140
	s_add_u32 s22, s22, 0x100000
	s_addc_u32 s23, s23, 0
	s_mov_b32 m0, s38
	v_lshl_add_u64 v[210:211], s[22:23], 0, v[166:167]
	ds_read_b128 v[144:147], v169 offset:32768
	ds_read_b128 v[148:151], v169 offset:33792
	ds_read_b128 v[152:155], v169 offset:34816
	ds_read_b128 v[156:159], v169 offset:35840
	ds_read_b128 v[176:179], v169 offset:36864
	ds_read_b128 v[180:183], v169 offset:37888
	ds_read_b128 v[186:189], v169 offset:38912
	ds_read_b128 v[206:209], v169 offset:39936
	global_load_lds_dwordx4 v[210:211], off
	v_lshl_add_u64 v[210:211], s[22:23], 0, v[162:163]
	s_mov_b32 m0, s39
	s_nop 0
	global_load_lds_dwordx4 v[210:211], off
	s_waitcnt lgkmcnt(8)
	s_barrier
	s_waitcnt lgkmcnt(0)
	s_setprio 1
	s_waitcnt lgkmcnt(0)
	v_mfma_f32_16x16x32_bf16 v[132:135], v[120:123], v[144:147], v[132:135]
	v_mfma_f32_16x16x32_bf16 v[128:131], v[136:139], v[144:147], v[128:131]
	v_mfma_f32_16x16x32_bf16 v[108:111], v[120:123], v[152:155], v[108:111]
	v_mfma_f32_16x16x32_bf16 v[104:107], v[136:139], v[152:155], v[104:107]
	v_mfma_f32_16x16x32_bf16 v[96:99], v[120:123], v[176:179], v[96:99]
	v_mfma_f32_16x16x32_bf16 v[88:91], v[136:139], v[176:179], v[88:91]
	v_mfma_f32_16x16x32_bf16 v[80:83], v[120:123], v[186:189], v[80:83]
	v_mfma_f32_16x16x32_bf16 v[72:75], v[136:139], v[186:189], v[72:75]
	v_mfma_f32_16x16x32_bf16 v[132:135], v[124:127], v[148:151], v[132:135]
	v_mfma_f32_16x16x32_bf16 v[128:131], v[140:143], v[148:151], v[128:131]
	v_mfma_f32_16x16x32_bf16 v[108:111], v[124:127], v[156:159], v[108:111]
	v_mfma_f32_16x16x32_bf16 v[104:107], v[140:143], v[156:159], v[104:107]
	v_mfma_f32_16x16x32_bf16 v[96:99], v[124:127], v[180:183], v[96:99]
	v_mfma_f32_16x16x32_bf16 v[88:91], v[140:143], v[180:183], v[88:91]
	v_mfma_f32_16x16x32_bf16 v[80:83], v[124:127], v[206:209], v[80:83]
	v_mfma_f32_16x16x32_bf16 v[72:75], v[140:143], v[206:209], v[72:75]
	s_setprio 0
	s_barrier
	v_or_b32_e32 v185, 0x1c000, v184
	s_mov_b32 m0, s41
	v_add_u32_e32 v192, 0x1c400, v184
	ds_read_b128 v[210:213], v185
	ds_read_b128 v[214:217], v192
	v_add_u32_e32 v185, 0x1c800, v184
	v_lshl_add_u64 v[190:191], v[190:191], 0, s[94:95]
	v_add_u32_e32 v192, 0x1cc00, v184
	ds_read_b128 v[244:247], v185
	ds_read_b128 v[248:251], v192
	global_load_lds_dwordx4 v[190:191], off
	v_lshl_add_u64 v[190:191], v[218:219], 0, s[94:95]
	s_mov_b32 m0, s42
	s_nop 0
	global_load_lds_dwordx4 v[190:191], off
	s_barrier
	s_waitcnt lgkmcnt(0)
	s_setprio 1
	s_waitcnt lgkmcnt(0)
	v_mfma_f32_16x16x32_bf16 v[116:119], v[210:213], v[144:147], v[116:119]
	v_mfma_f32_16x16x32_bf16 v[112:115], v[244:247], v[144:147], v[112:115]
	v_mfma_f32_16x16x32_bf16 v[100:103], v[210:213], v[152:155], v[100:103]
	v_mfma_f32_16x16x32_bf16 v[92:95], v[244:247], v[152:155], v[92:95]
	v_mfma_f32_16x16x32_bf16 v[84:87], v[210:213], v[176:179], v[84:87]
	v_mfma_f32_16x16x32_bf16 v[76:79], v[244:247], v[176:179], v[76:79]
	v_mfma_f32_16x16x32_bf16 v[68:71], v[210:213], v[186:189], v[68:71]
	v_mfma_f32_16x16x32_bf16 v[64:67], v[244:247], v[186:189], v[64:67]
	v_mfma_f32_16x16x32_bf16 v[116:119], v[214:217], v[148:151], v[116:119]
	v_mfma_f32_16x16x32_bf16 v[112:115], v[248:251], v[148:151], v[112:115]
	v_mfma_f32_16x16x32_bf16 v[100:103], v[214:217], v[156:159], v[100:103]
	v_mfma_f32_16x16x32_bf16 v[92:95], v[248:251], v[156:159], v[92:95]
	v_mfma_f32_16x16x32_bf16 v[84:87], v[214:217], v[180:183], v[84:87]
	v_mfma_f32_16x16x32_bf16 v[76:79], v[248:251], v[180:183], v[76:79]
	v_mfma_f32_16x16x32_bf16 v[68:71], v[214:217], v[206:209], v[68:71]
	v_mfma_f32_16x16x32_bf16 v[64:67], v[248:251], v[206:209], v[64:67]
	s_setprio 0
	s_mov_b32 m0, s43
	v_lshl_add_u64 v[190:191], v[228:229], 0, s[94:95]
	s_barrier
	ds_read_b128 v[144:147], v169 offset:49152
	ds_read_b128 v[148:151], v169 offset:50176
	ds_read_b128 v[152:155], v169 offset:51200
	ds_read_b128 v[156:159], v169 offset:52224
	ds_read_b128 v[176:179], v169 offset:53248
	ds_read_b128 v[180:183], v169 offset:54272
	ds_read_b128 v[186:189], v169 offset:55296
	ds_read_b128 v[206:209], v169 offset:56320
	global_load_lds_dwordx4 v[190:191], off
	v_lshl_add_u64 v[190:191], v[232:233], 0, s[94:95]
	s_mov_b32 m0, s44
	s_nop 0
	global_load_lds_dwordx4 v[190:191], off
	s_barrier
	s_waitcnt lgkmcnt(0)
	s_setprio 1
	s_waitcnt lgkmcnt(0)
	v_mfma_f32_16x16x32_bf16 v[60:63], v[120:123], v[144:147], v[60:63]
	v_mfma_f32_16x16x32_bf16 v[56:59], v[136:139], v[144:147], v[56:59]
	v_mfma_f32_16x16x32_bf16 v[48:51], v[120:123], v[152:155], v[48:51]
	v_mfma_f32_16x16x32_bf16 v[40:43], v[136:139], v[152:155], v[40:43]
	v_mfma_f32_16x16x32_bf16 v[32:35], v[120:123], v[176:179], v[32:35]
	v_mfma_f32_16x16x32_bf16 v[24:27], v[136:139], v[176:179], v[24:27]
	v_mfma_f32_16x16x32_bf16 v[16:19], v[120:123], v[186:189], v[16:19]
	v_mfma_f32_16x16x32_bf16 v[8:11], v[136:139], v[186:189], v[8:11]
	v_mfma_f32_16x16x32_bf16 v[60:63], v[124:127], v[148:151], v[60:63]
	v_mfma_f32_16x16x32_bf16 v[56:59], v[140:143], v[148:151], v[56:59]
	v_mfma_f32_16x16x32_bf16 v[48:51], v[124:127], v[156:159], v[48:51]
	v_mfma_f32_16x16x32_bf16 v[40:43], v[140:143], v[156:159], v[40:43]
	v_mfma_f32_16x16x32_bf16 v[32:35], v[124:127], v[180:183], v[32:35]
	v_mfma_f32_16x16x32_bf16 v[24:27], v[140:143], v[180:183], v[24:27]
	v_mfma_f32_16x16x32_bf16 v[16:19], v[124:127], v[206:209], v[16:19]
	v_mfma_f32_16x16x32_bf16 v[8:11], v[140:143], v[206:209], v[8:11]
	s_setprio 0
	s_barrier
	s_add_u32 s20, s20, 0x100080
	s_addc_u32 s21, s21, 0
	s_mov_b32 m0, s45
	v_lshl_add_u64 v[120:121], s[20:21], 0, v[164:165]
	global_load_lds_dwordx4 v[120:121], off
	v_lshl_add_u64 v[120:121], s[20:21], 0, v[160:161]
	s_mov_b32 m0, s46
	s_nop 0
	global_load_lds_dwordx4 v[120:121], off
	s_waitcnt vmcnt(6)
	s_barrier
	s_setprio 1
	v_mfma_f32_16x16x32_bf16 v[52:55], v[210:213], v[144:147], v[52:55]
	v_mfma_f32_16x16x32_bf16 v[44:47], v[244:247], v[144:147], v[44:47]
	v_mfma_f32_16x16x32_bf16 v[36:39], v[210:213], v[152:155], v[36:39]
	v_mfma_f32_16x16x32_bf16 v[28:31], v[244:247], v[152:155], v[28:31]
	v_mfma_f32_16x16x32_bf16 v[20:23], v[210:213], v[176:179], v[20:23]
	v_mfma_f32_16x16x32_bf16 v[12:15], v[244:247], v[176:179], v[12:15]
	v_mfma_f32_16x16x32_bf16 v[4:7], v[210:213], v[186:189], v[4:7]
	v_mfma_f32_16x16x32_bf16 v[0:3], v[244:247], v[186:189], v[0:3]
	v_mfma_f32_16x16x32_bf16 v[52:55], v[214:217], v[148:151], v[52:55]
	v_mfma_f32_16x16x32_bf16 v[44:47], v[248:251], v[148:151], v[44:47]
	v_mfma_f32_16x16x32_bf16 v[36:39], v[214:217], v[156:159], v[36:39]
	v_mfma_f32_16x16x32_bf16 v[28:31], v[248:251], v[156:159], v[28:31]
	v_mfma_f32_16x16x32_bf16 v[20:23], v[214:217], v[180:183], v[20:23]
	v_mfma_f32_16x16x32_bf16 v[12:15], v[248:251], v[180:183], v[12:15]
	v_mfma_f32_16x16x32_bf16 v[4:7], v[214:217], v[206:209], v[4:7]
	v_mfma_f32_16x16x32_bf16 v[0:3], v[248:251], v[206:209], v[0:3]
	s_setprio 0
	s_add_i32 s67, s67, 2
	s_add_u32 s18, s18, 0x100
	s_addc_u32 s19, s19, 0
	s_add_u32 s65, s65, 0x100
	s_addc_u32 s66, s66, 0
	s_cmp_gt_u32 s67, 61
	s_barrier
	s_cbranch_scc0 .LBB0_1054
	s_lshl_b32 s18, s16, 8
	s_add_i32 s5, s18, 0xffff0000
	s_lshr_b32 s5, s5, 13
	s_add_i32 s5, s5, 16
	s_ashr_i32 s7, s16, 4
	s_cmpk_lt_i32 s16, 0x100
	s_cselect_b32 s5, s7, s5
	v_readlane_b32 s7, v254, 44
	s_add_i32 s5, s5, s7
	s_mul_hi_i32 s7, s5, 0x6000
	s_mulk_i32 s5, 0x6000
	v_readlane_b32 s16, v254, 29
	s_add_u32 s5, s16, s5
	v_readlane_b32 s16, v254, 30
	s_addc_u32 s7, s16, s7
	s_lshl_b32 s20, s0, 8
	s_ashr_i32 s21, s20, 31
	s_lshl_b64 s[16:17], s[20:21], 2
	s_add_u32 s0, s5, s16
	s_addc_u32 s5, s7, s17
	s_lshl_b32 s7, s40, 2
	s_add_u32 s16, s0, s7
	s_addc_u32 s17, s5, 0
	s_ashr_i32 s19, s18, 31
	s_lshl_b64 s[18:19], s[18:19], 11
	v_lshl_add_u64 v[120:121], v[170:171], 0, s[18:19]
	v_lshl_add_u64 v[120:121], s[20:21], 1, v[120:121]
	s_lshl_b32 s0, s40, 1
	v_lshl_add_u64 v[120:121], v[120:121], 0, s[0:1]
	v_lshlrev_b32_e32 v192, 1, v168
	v_lshl_add_u64 v[176:177], v[120:121], 0, v[192:193]
	v_add_co_u32_e32 v182, vcc, s70, v176
	s_mov_b32 s0, 0x10000
	s_nop 0
	v_addc_co_u32_e32 v183, vcc, 0, v177, vcc
	v_add_co_u32_e32 v180, vcc, s0, v176
	s_mov_b32 s0, 0x18000
	s_nop 0
	v_addc_co_u32_e32 v181, vcc, 0, v177, vcc
	v_add_co_u32_e32 v178, vcc, s0, v176
	v_lshlrev_b32_e32 v185, 2, v168
	s_nop 0
	v_addc_co_u32_e32 v179, vcc, 0, v177, vcc
	global_load_dwordx4 v[186:189], v[176:177], off
	global_load_dwordx4 v[206:209], v[176:177], off offset:256
	global_load_dwordx4 v[156:159], v[182:183], off
	global_load_dwordx4 v[152:155], v[182:183], off offset:256
	global_load_dwordx4 v[148:151], v[180:181], off
	global_load_dwordx4 v[144:147], v[180:181], off offset:256
	global_load_dwordx4 v[140:143], v[178:179], off
	global_load_dwordx4 v[136:139], v[178:179], off offset:256
	global_load_dwordx4 v[120:123], v185, s[16:17] offset:16
	global_load_dwordx4 v[124:127], v185, s[16:17]
	global_load_dwordx4 v[244:247], v185, s[16:17] offset:528
	global_load_dwordx4 v[248:251], v185, s[16:17] offset:512
	s_mov_b32 s98, 0x40000
	s_mov_b32 s99, 0
	v_lshl_add_u64 v[218:219], v[176:177], 0, s[98:99]
	global_load_dwordx4 v[210:213], v[218:219], off
	global_load_dwordx4 v[214:217], v[218:219], off offset:256
	s_mov_b32 s0, 0x40000
	s_mov_b64 s[20:21], s[14:15]
	s_mov_b64 s[18:19], s[12:13]
	s_waitcnt vmcnt(2)
	v_lshlrev_b32_e32 v190, 16, v186
	v_and_b32_e32 v191, 0xffff0000, v186
	v_pk_fma_f32 v[132:133], v[132:133], v[124:125], v[190:191]
	s_nop 0
	v_cvt_pk_bf16_f32 v186, v132, v133
	v_lshlrev_b32_e32 v132, 16, v187
	v_and_b32_e32 v133, 0xffff0000, v187
	v_pk_fma_f32 v[132:133], v[134:135], v[126:127], v[132:133]
	v_lshlrev_b32_e32 v190, 16, v206
	v_cvt_pk_bf16_f32 v187, v132, v133
	v_lshlrev_b32_e32 v132, 16, v188
	v_and_b32_e32 v133, 0xffff0000, v188
	v_pk_fma_f32 v[128:129], v[128:129], v[120:121], v[132:133]
	v_and_b32_e32 v191, 0xffff0000, v206
	v_cvt_pk_bf16_f32 v188, v128, v129
	v_lshlrev_b32_e32 v128, 16, v189
	v_and_b32_e32 v129, 0xffff0000, v189
	v_pk_fma_f32 v[128:129], v[130:131], v[122:123], v[128:129]
	s_nop 0
	v_cvt_pk_bf16_f32 v189, v128, v129
	v_mov_b32_e32 v128, v244
	v_mov_b32_e32 v129, v245
	v_mov_b32_e32 v130, v246
	v_mov_b32_e32 v131, v247
	v_mov_b32_e32 v132, v248
	v_mov_b32_e32 v133, v249
	v_mov_b32_e32 v134, v250
	v_mov_b32_e32 v135, v251
	global_store_dwordx4 v[176:177], v[186:189], off
	s_mov_b32 s16, s6
	v_pk_fma_f32 v[116:117], v[116:117], v[132:133], v[190:191]
	v_lshlrev_b32_e32 v190, 16, v207
	v_and_b32_e32 v191, 0xffff0000, v207
	v_pk_fma_f32 v[118:119], v[118:119], v[134:135], v[190:191]
	v_cvt_pk_bf16_f32 v116, v116, v117
	v_cvt_pk_bf16_f32 v117, v118, v119
	v_lshlrev_b32_e32 v118, 16, v208
	v_and_b32_e32 v119, 0xffff0000, v208
	v_pk_fma_f32 v[112:113], v[112:113], v[128:129], v[118:119]
	s_nop 0
	v_cvt_pk_bf16_f32 v118, v112, v113
	v_lshlrev_b32_e32 v112, 16, v209
	v_and_b32_e32 v113, 0xffff0000, v209
	s_mov_b32 s98, 0x48000
	s_mov_b32 s99, 0
	v_lshl_add_u64 v[228:229], v[176:177], 0, s[98:99]
	global_load_dwordx4 v[206:209], v[228:229], off
	v_pk_fma_f32 v[112:113], v[114:115], v[130:131], v[112:113]
	s_nop 0
	v_cvt_pk_bf16_f32 v119, v112, v113
	v_lshlrev_b32_e32 v112, 16, v156
	v_and_b32_e32 v113, 0xffff0000, v156
	v_pk_fma_f32 v[108:109], v[108:109], v[124:125], v[112:113]
	v_lshlrev_b32_e32 v112, 16, v157
	v_and_b32_e32 v113, 0xffff0000, v157
	v_pk_fma_f32 v[110:111], v[110:111], v[126:127], v[112:113]
	v_cvt_pk_bf16_f32 v108, v108, v109
	v_cvt_pk_bf16_f32 v109, v110, v111
	v_lshlrev_b32_e32 v110, 16, v158
	v_and_b32_e32 v111, 0xffff0000, v158
	v_pk_fma_f32 v[104:105], v[104:105], v[120:121], v[110:111]
	global_store_dwordx4 v[176:177], v[116:119], off offset:256
	v_cvt_pk_bf16_f32 v110, v104, v105
	v_lshlrev_b32_e32 v104, 16, v159
	v_and_b32_e32 v105, 0xffff0000, v159
	global_load_dwordx4 v[156:159], v[228:229], off offset:256
	v_pk_fma_f32 v[104:105], v[106:107], v[122:123], v[104:105]
	s_nop 0
	v_cvt_pk_bf16_f32 v111, v104, v105
	v_lshlrev_b32_e32 v104, 16, v152
	v_and_b32_e32 v105, 0xffff0000, v152
	v_pk_fma_f32 v[100:101], v[100:101], v[132:133], v[104:105]
	v_lshlrev_b32_e32 v104, 16, v153
	v_and_b32_e32 v105, 0xffff0000, v153
	v_pk_fma_f32 v[102:103], v[102:103], v[134:135], v[104:105]
	v_cvt_pk_bf16_f32 v100, v100, v101
	v_cvt_pk_bf16_f32 v101, v102, v103
	v_lshlrev_b32_e32 v102, 16, v154
	v_and_b32_e32 v103, 0xffff0000, v154
	v_pk_fma_f32 v[92:93], v[92:93], v[128:129], v[102:103]
	global_store_dwordx4 v[182:183], v[108:111], off
	v_cvt_pk_bf16_f32 v102, v92, v93
	v_lshlrev_b32_e32 v92, 16, v155
	v_and_b32_e32 v93, 0xffff0000, v155
	s_mov_b32 s98, 0x50000
	s_mov_b32 s99, 0
	v_lshl_add_u64 v[232:233], v[176:177], 0, s[98:99]
	global_load_dwordx4 v[152:155], v[232:233], off
	v_pk_fma_f32 v[92:93], v[94:95], v[130:131], v[92:93]
	v_lshlrev_b32_e32 v94, 16, v149
	v_cvt_pk_bf16_f32 v103, v92, v93
	v_lshlrev_b32_e32 v92, 16, v148
	v_and_b32_e32 v93, 0xffff0000, v148
	v_and_b32_e32 v95, 0xffff0000, v149
	v_pk_fma_f32 v[92:93], v[96:97], v[124:125], v[92:93]
	v_pk_fma_f32 v[94:95], v[98:99], v[126:127], v[94:95]
	v_cvt_pk_bf16_f32 v92, v92, v93
	v_cvt_pk_bf16_f32 v93, v94, v95
	v_lshlrev_b32_e32 v94, 16, v150
	v_and_b32_e32 v95, 0xffff0000, v150
	v_pk_fma_f32 v[88:89], v[88:89], v[120:121], v[94:95]
	global_store_dwordx4 v[182:183], v[100:103], off offset:256
	v_cvt_pk_bf16_f32 v94, v88, v89
	v_lshlrev_b32_e32 v88, 16, v151
	v_and_b32_e32 v89, 0xffff0000, v151
	global_load_dwordx4 v[148:151], v[232:233], off offset:256
	v_pk_fma_f32 v[88:89], v[90:91], v[122:123], v[88:89]
	v_add_co_u32_e32 v98, vcc, s0, v176
	v_cvt_pk_bf16_f32 v95, v88, v89
	v_lshlrev_b32_e32 v88, 16, v144
	v_and_b32_e32 v89, 0xffff0000, v144
	v_pk_fma_f32 v[84:85], v[84:85], v[132:133], v[88:89]
	v_lshlrev_b32_e32 v88, 16, v145
	v_and_b32_e32 v89, 0xffff0000, v145
	v_pk_fma_f32 v[86:87], v[86:87], v[134:135], v[88:89]
	v_cvt_pk_bf16_f32 v84, v84, v85
	v_cvt_pk_bf16_f32 v85, v86, v87
	v_lshlrev_b32_e32 v86, 16, v146
	v_and_b32_e32 v87, 0xffff0000, v146
	v_pk_fma_f32 v[76:77], v[76:77], v[128:129], v[86:87]
	global_store_dwordx4 v[180:181], v[92:95], off
	v_cvt_pk_bf16_f32 v86, v76, v77
	v_lshlrev_b32_e32 v76, 16, v147
	v_and_b32_e32 v77, 0xffff0000, v147
	s_mov_b32 s98, 0x58000
	s_mov_b32 s99, 0
	v_lshl_add_u64 v[218:219], v[176:177], 0, s[98:99]
	global_load_dwordx4 v[144:147], v[218:219], off
	v_pk_fma_f32 v[76:77], v[78:79], v[130:131], v[76:77]
	v_lshlrev_b32_e32 v78, 16, v141
	v_cvt_pk_bf16_f32 v87, v76, v77
	v_lshlrev_b32_e32 v76, 16, v140
	v_and_b32_e32 v77, 0xffff0000, v140
	v_and_b32_e32 v79, 0xffff0000, v141
	v_pk_fma_f32 v[76:77], v[80:81], v[124:125], v[76:77]
	v_pk_fma_f32 v[78:79], v[82:83], v[126:127], v[78:79]
	v_cvt_pk_bf16_f32 v76, v76, v77
	v_cvt_pk_bf16_f32 v77, v78, v79
	v_lshlrev_b32_e32 v78, 16, v142
	v_and_b32_e32 v79, 0xffff0000, v142
	v_pk_fma_f32 v[72:73], v[72:73], v[120:121], v[78:79]
	global_store_dwordx4 v[180:181], v[84:87], off offset:256
	v_cvt_pk_bf16_f32 v78, v72, v73
	v_lshlrev_b32_e32 v72, 16, v143
	v_and_b32_e32 v73, 0xffff0000, v143
	global_load_dwordx4 v[140:143], v[218:219], off offset:256
	v_pk_fma_f32 v[72:73], v[74:75], v[122:123], v[72:73]
	v_addc_co_u32_e32 v99, vcc, 0, v177, vcc
	v_cvt_pk_bf16_f32 v79, v72, v73
	v_lshlrev_b32_e32 v72, 16, v136
	v_and_b32_e32 v73, 0xffff0000, v136
	v_pk_fma_f32 v[68:69], v[68:69], v[132:133], v[72:73]
	v_lshlrev_b32_e32 v72, 16, v137
	v_and_b32_e32 v73, 0xffff0000, v137
	v_pk_fma_f32 v[70:71], v[70:71], v[134:135], v[72:73]
	v_cvt_pk_bf16_f32 v68, v68, v69
	v_cvt_pk_bf16_f32 v69, v70, v71
	v_lshlrev_b32_e32 v70, 16, v138
	v_and_b32_e32 v71, 0xffff0000, v138
	v_pk_fma_f32 v[64:65], v[64:65], v[128:129], v[70:71]
	global_store_dwordx4 v[178:179], v[76:79], off
	v_cvt_pk_bf16_f32 v70, v64, v65
	v_lshlrev_b32_e32 v64, 16, v139
	v_and_b32_e32 v65, 0xffff0000, v139
	v_pk_fma_f32 v[64:65], v[66:67], v[130:131], v[64:65]
	s_mov_b32 s0, 0x48000
	v_cvt_pk_bf16_f32 v71, v64, v65
	global_store_dwordx4 v[178:179], v[68:71], off offset:256
	v_add_co_u32_e32 v100, vcc, s0, v176
	s_mov_b32 s0, 0x50000
	s_nop 0
	v_addc_co_u32_e32 v101, vcc, 0, v177, vcc
	v_add_co_u32_e32 v102, vcc, s0, v176
	s_mov_b32 s0, 0x58000
	s_nop 0
	v_addc_co_u32_e32 v103, vcc, 0, v177, vcc
	v_add_co_u32_e32 v68, vcc, s0, v176
	s_mov_b32 s0, s4
	s_nop 0
	v_addc_co_u32_e32 v69, vcc, 0, v177, vcc
	s_and_b64 vcc, exec, s[2:3]
	s_waitcnt vmcnt(2)
	v_mov_b32_e32 v70, v210
	v_mov_b32_e32 v71, v211
	v_mov_b32_e32 v72, v212
	v_mov_b32_e32 v73, v213
	v_mov_b32_e32 v74, v214
	v_mov_b32_e32 v75, v215
	v_mov_b32_e32 v76, v216
	v_mov_b32_e32 v77, v217
	v_mov_b32_e32 v78, v206
	v_mov_b32_e32 v79, v207
	v_mov_b32_e32 v80, v208
	v_mov_b32_e32 v81, v209
	v_mov_b32_e32 v82, v156
	v_mov_b32_e32 v83, v157
	v_mov_b32_e32 v84, v158
	v_mov_b32_e32 v85, v159
	v_mov_b32_e32 v86, v152
	v_mov_b32_e32 v87, v153
	v_mov_b32_e32 v88, v154
	v_mov_b32_e32 v89, v155
	v_mov_b32_e32 v90, v148
	v_mov_b32_e32 v91, v149
	v_mov_b32_e32 v92, v150
	v_mov_b32_e32 v93, v151
	v_mov_b32_e32 v94, v144
	v_mov_b32_e32 v95, v145
	v_mov_b32_e32 v96, v146
	v_mov_b32_e32 v97, v147
	v_mov_b32_e32 v64, v140
	v_mov_b32_e32 v65, v141
	v_mov_b32_e32 v66, v142
	v_mov_b32_e32 v67, v143
	v_lshlrev_b32_e32 v104, 16, v70
	v_and_b32_e32 v105, 0xffff0000, v70
	v_lshlrev_b32_e32 v70, 16, v71
	v_and_b32_e32 v71, 0xffff0000, v71
	v_pk_fma_f32 v[60:61], v[60:61], v[124:125], v[104:105]
	v_pk_fma_f32 v[62:63], v[62:63], v[126:127], v[70:71]
	v_cvt_pk_bf16_f32 v60, v60, v61
	v_cvt_pk_bf16_f32 v61, v62, v63
	v_lshlrev_b32_e32 v62, 16, v72
	v_and_b32_e32 v63, 0xffff0000, v72
	v_pk_fma_f32 v[56:57], v[56:57], v[120:121], v[62:63]
	s_nop 0
	v_cvt_pk_bf16_f32 v62, v56, v57
	v_lshlrev_b32_e32 v56, 16, v73
	v_and_b32_e32 v57, 0xffff0000, v73
	v_pk_fma_f32 v[56:57], v[58:59], v[122:123], v[56:57]
	s_nop 0
	v_cvt_pk_bf16_f32 v63, v56, v57
	v_lshlrev_b32_e32 v56, 16, v74
	v_and_b32_e32 v57, 0xffff0000, v74
	v_pk_fma_f32 v[52:53], v[52:53], v[132:133], v[56:57]
	v_lshlrev_b32_e32 v56, 16, v75
	v_and_b32_e32 v57, 0xffff0000, v75
	v_pk_fma_f32 v[54:55], v[54:55], v[134:135], v[56:57]
	v_cvt_pk_bf16_f32 v52, v52, v53
	v_cvt_pk_bf16_f32 v53, v54, v55
	v_lshlrev_b32_e32 v54, 16, v76
	v_and_b32_e32 v55, 0xffff0000, v76
	v_pk_fma_f32 v[44:45], v[44:45], v[128:129], v[54:55]
	global_store_dwordx4 v[98:99], v[60:63], off
	v_cvt_pk_bf16_f32 v54, v44, v45
	v_lshlrev_b32_e32 v44, 16, v77
	v_and_b32_e32 v45, 0xffff0000, v77
	v_pk_fma_f32 v[44:45], v[46:47], v[130:131], v[44:45]
	v_lshlrev_b32_e32 v46, 16, v79
	v_cvt_pk_bf16_f32 v55, v44, v45
	v_lshlrev_b32_e32 v44, 16, v78
	v_and_b32_e32 v45, 0xffff0000, v78
	v_and_b32_e32 v47, 0xffff0000, v79
	v_pk_fma_f32 v[44:45], v[48:49], v[124:125], v[44:45]
	v_pk_fma_f32 v[46:47], v[50:51], v[126:127], v[46:47]
	v_cvt_pk_bf16_f32 v44, v44, v45
	v_cvt_pk_bf16_f32 v45, v46, v47
	v_lshlrev_b32_e32 v46, 16, v80
	v_and_b32_e32 v47, 0xffff0000, v80
	v_pk_fma_f32 v[40:41], v[40:41], v[120:121], v[46:47]
	global_store_dwordx4 v[98:99], v[52:55], off offset:256
	v_cvt_pk_bf16_f32 v46, v40, v41
	v_lshlrev_b32_e32 v40, 16, v81
	v_and_b32_e32 v41, 0xffff0000, v81
	v_pk_fma_f32 v[40:41], v[42:43], v[122:123], v[40:41]
	s_nop 0
	v_cvt_pk_bf16_f32 v47, v40, v41
	v_lshlrev_b32_e32 v40, 16, v82
	v_and_b32_e32 v41, 0xffff0000, v82
	v_pk_fma_f32 v[36:37], v[36:37], v[132:133], v[40:41]
	v_lshlrev_b32_e32 v40, 16, v83
	v_and_b32_e32 v41, 0xffff0000, v83
	v_pk_fma_f32 v[38:39], v[38:39], v[134:135], v[40:41]
	v_cvt_pk_bf16_f32 v36, v36, v37
	v_cvt_pk_bf16_f32 v37, v38, v39
	v_lshlrev_b32_e32 v38, 16, v84
	v_and_b32_e32 v39, 0xffff0000, v84
	v_pk_fma_f32 v[28:29], v[28:29], v[128:129], v[38:39]
	global_store_dwordx4 v[100:101], v[44:47], off
	v_cvt_pk_bf16_f32 v38, v28, v29
	v_lshlrev_b32_e32 v28, 16, v85
	v_and_b32_e32 v29, 0xffff0000, v85
	v_pk_fma_f32 v[28:29], v[30:31], v[130:131], v[28:29]
	v_lshlrev_b32_e32 v30, 16, v87
	v_cvt_pk_bf16_f32 v39, v28, v29
	v_lshlrev_b32_e32 v28, 16, v86
	v_and_b32_e32 v29, 0xffff0000, v86
	v_and_b32_e32 v31, 0xffff0000, v87
	v_pk_fma_f32 v[28:29], v[32:33], v[124:125], v[28:29]
	v_pk_fma_f32 v[30:31], v[34:35], v[126:127], v[30:31]
	v_cvt_pk_bf16_f32 v28, v28, v29
	v_cvt_pk_bf16_f32 v29, v30, v31
	v_lshlrev_b32_e32 v30, 16, v88
	v_and_b32_e32 v31, 0xffff0000, v88
	v_pk_fma_f32 v[24:25], v[24:25], v[120:121], v[30:31]
	global_store_dwordx4 v[100:101], v[36:39], off offset:256
	v_cvt_pk_bf16_f32 v30, v24, v25
	v_lshlrev_b32_e32 v24, 16, v89
	v_and_b32_e32 v25, 0xffff0000, v89
	v_pk_fma_f32 v[24:25], v[26:27], v[122:123], v[24:25]
	s_nop 0
	v_cvt_pk_bf16_f32 v31, v24, v25
	v_lshlrev_b32_e32 v24, 16, v90
	v_and_b32_e32 v25, 0xffff0000, v90
	v_pk_fma_f32 v[20:21], v[20:21], v[132:133], v[24:25]
	v_lshlrev_b32_e32 v24, 16, v91
	v_and_b32_e32 v25, 0xffff0000, v91
	v_pk_fma_f32 v[22:23], v[22:23], v[134:135], v[24:25]
	v_cvt_pk_bf16_f32 v20, v20, v21
	v_cvt_pk_bf16_f32 v21, v22, v23
	v_lshlrev_b32_e32 v22, 16, v92
	v_and_b32_e32 v23, 0xffff0000, v92
	v_pk_fma_f32 v[12:13], v[12:13], v[128:129], v[22:23]
	global_store_dwordx4 v[102:103], v[28:31], off
	v_cvt_pk_bf16_f32 v22, v12, v13
	v_lshlrev_b32_e32 v12, 16, v93
	v_and_b32_e32 v13, 0xffff0000, v93
	v_pk_fma_f32 v[12:13], v[14:15], v[130:131], v[12:13]
	v_lshlrev_b32_e32 v14, 16, v95
	v_cvt_pk_bf16_f32 v23, v12, v13
	v_lshlrev_b32_e32 v12, 16, v94
	v_and_b32_e32 v13, 0xffff0000, v94
	v_and_b32_e32 v15, 0xffff0000, v95
	v_pk_fma_f32 v[12:13], v[16:17], v[124:125], v[12:13]
	v_pk_fma_f32 v[14:15], v[18:19], v[126:127], v[14:15]
	v_cvt_pk_bf16_f32 v12, v12, v13
	v_cvt_pk_bf16_f32 v13, v14, v15
	v_lshlrev_b32_e32 v14, 16, v96
	v_and_b32_e32 v15, 0xffff0000, v96
	v_pk_fma_f32 v[8:9], v[8:9], v[120:121], v[14:15]
	global_store_dwordx4 v[102:103], v[20:23], off offset:256
	v_cvt_pk_bf16_f32 v14, v8, v9
	v_lshlrev_b32_e32 v8, 16, v97
	v_and_b32_e32 v9, 0xffff0000, v97
	v_pk_fma_f32 v[8:9], v[10:11], v[122:123], v[8:9]
	s_nop 0
	v_cvt_pk_bf16_f32 v15, v8, v9
	v_lshlrev_b32_e32 v8, 16, v64
	v_and_b32_e32 v9, 0xffff0000, v64
	v_pk_fma_f32 v[4:5], v[4:5], v[132:133], v[8:9]
	v_lshlrev_b32_e32 v8, 16, v65
	v_and_b32_e32 v9, 0xffff0000, v65
	v_pk_fma_f32 v[6:7], v[6:7], v[134:135], v[8:9]
	v_cvt_pk_bf16_f32 v4, v4, v5
	v_cvt_pk_bf16_f32 v5, v6, v7
	v_lshlrev_b32_e32 v6, 16, v66
	v_and_b32_e32 v7, 0xffff0000, v66
	v_pk_fma_f32 v[0:1], v[0:1], v[128:129], v[6:7]
	global_store_dwordx4 v[68:69], v[12:15], off
	v_cvt_pk_bf16_f32 v6, v0, v1
	v_lshlrev_b32_e32 v0, 16, v67
	v_and_b32_e32 v1, 0xffff0000, v67
	v_pk_fma_f32 v[0:1], v[2:3], v[130:131], v[0:1]
	s_nop 0
	v_cvt_pk_bf16_f32 v7, v0, v1
	global_store_dwordx4 v[68:69], v[4:7], off offset:256
	s_cbranch_vccz .LBB0_1051
	s_waitcnt vmcnt(0)
	s_cmpk_gt_u32 s26, 0xff
	s_cbranch_scc1 .LBB0_1058
	s_barrier
